# attention score waves: LDS read ring deepened from 10 to 14 fragments (registers freed by moving the staging)
# baseline (speedup 1.0000x reference)
.LBB0_407:
.LBB0_409:
	s_cmp_ge_i32 s8, s27
	s_cbranch_scc1 .LBB0_413
	s_mul_hi_u32 s8, s8, 0xaaaaaaab
	s_lshr_b32 s8, s8, 1
	s_mul_i32 s8, s8, 0xfffe1400
	s_add_i32 s8, s28, s8
	v_add_u32_e32 v175, s8, v174
	ds_read_b128 v[176:179], v175
	ds_read_b128 v[180:183], v175 offset:32
	ds_read_b128 v[184:187], v175 offset:20992
	ds_read_b128 v[188:191], v175 offset:21024
	ds_read_b128 v[220:223], v175 offset:64
	ds_read_b128 v[224:227], v175 offset:21056
	ds_read_b128 v[228:231], v175 offset:96
	ds_read_b128 v[232:235], v175 offset:21088
	ds_read_b128 v[236:239], v175 offset:128
	ds_read_b128 v[240:243], v175 offset:21120
	ds_read_b128 v[114:117], v175 offset:160
	ds_read_b128 v[118:121], v175 offset:21152
	ds_read_b128 v[122:125], v175 offset:192
	ds_read_b128 v[126:129], v175 offset:21184
	s_mov_b32 s8, 0xf149f2ca
	s_waitcnt vmcnt(19) lgkmcnt(13)
	v_mfma_f32_32x32x16_bf16 v[18:33], v[176:179], v[34:37], 0
	ds_read_b128 v[176:179], v175 offset:224
	s_waitcnt vmcnt(18) lgkmcnt(13)
	v_mfma_f32_32x32x16_bf16 v[18:33], v[180:183], v[38:41], v[18:33]
	ds_read_b128 v[180:183], v175 offset:21216
	s_waitcnt lgkmcnt(13)
	v_mfma_f32_32x32x16_bf16 v[2:17], v[184:187], v[34:37], 0
	ds_read_b128 v[184:187], v175 offset:256
	s_waitcnt lgkmcnt(13)
	v_mfma_f32_32x32x16_bf16 v[2:17], v[188:191], v[38:41], v[2:17]
	ds_read_b128 v[188:191], v175 offset:21248
	s_waitcnt vmcnt(17) lgkmcnt(13)
	v_mfma_f32_32x32x16_bf16 v[18:33], v[220:223], v[42:45], v[18:33]
	ds_read_b128 v[220:223], v175 offset:288
	s_waitcnt lgkmcnt(13)
	v_mfma_f32_32x32x16_bf16 v[2:17], v[224:227], v[42:45], v[2:17]
	ds_read_b128 v[224:227], v175 offset:21280
	s_waitcnt vmcnt(16) lgkmcnt(13)
	v_mfma_f32_32x32x16_bf16 v[18:33], v[228:231], v[46:49], v[18:33]
	ds_read_b128 v[228:231], v175 offset:320
	s_waitcnt lgkmcnt(13)
	v_mfma_f32_32x32x16_bf16 v[2:17], v[232:235], v[46:49], v[2:17]
	ds_read_b128 v[232:235], v175 offset:21312
	s_waitcnt vmcnt(15) lgkmcnt(13)
	v_mfma_f32_32x32x16_bf16 v[18:33], v[236:239], v[50:53], v[18:33]
	ds_read_b128 v[236:239], v175 offset:352
	s_waitcnt lgkmcnt(13)
	v_mfma_f32_32x32x16_bf16 v[2:17], v[240:243], v[50:53], v[2:17]
	ds_read_b128 v[240:243], v175 offset:21344
	s_waitcnt vmcnt(14) lgkmcnt(13)
	v_mfma_f32_32x32x16_bf16 v[18:33], v[114:117], v[54:57], v[18:33]
	ds_read_b128 v[114:117], v175 offset:384
	s_waitcnt lgkmcnt(13)
	v_mfma_f32_32x32x16_bf16 v[2:17], v[118:121], v[54:57], v[2:17]
	ds_read_b128 v[118:121], v175 offset:21376
	s_waitcnt vmcnt(13) lgkmcnt(13)
	v_mfma_f32_32x32x16_bf16 v[18:33], v[122:125], v[58:61], v[18:33]
	ds_read_b128 v[122:125], v175 offset:416
	s_waitcnt lgkmcnt(13)
	v_mfma_f32_32x32x16_bf16 v[2:17], v[126:129], v[58:61], v[2:17]
	ds_read_b128 v[126:129], v175 offset:21408
	s_waitcnt vmcnt(12) lgkmcnt(13)
	v_mfma_f32_32x32x16_bf16 v[18:33], v[176:179], v[62:65], v[18:33]
	ds_read_b128 v[176:179], v175 offset:448
	s_waitcnt lgkmcnt(13)
	v_mfma_f32_32x32x16_bf16 v[2:17], v[180:183], v[62:65], v[2:17]
	ds_read_b128 v[180:183], v175 offset:21440
	s_waitcnt vmcnt(11) lgkmcnt(13)
	v_mfma_f32_32x32x16_bf16 v[18:33], v[184:187], v[66:69], v[18:33]
	ds_read_b128 v[184:187], v175 offset:480
	s_waitcnt lgkmcnt(13)
	v_mfma_f32_32x32x16_bf16 v[2:17], v[188:191], v[66:69], v[2:17]
	ds_read_b128 v[188:191], v175 offset:21472
	s_waitcnt vmcnt(10) lgkmcnt(13)
	v_mfma_f32_32x32x16_bf16 v[18:33], v[220:223], v[70:73], v[18:33]
	ds_read_b128 v[220:223], v175 offset:512
	s_waitcnt lgkmcnt(13)
	v_mfma_f32_32x32x16_bf16 v[2:17], v[224:227], v[70:73], v[2:17]
	ds_read_b128 v[224:227], v175 offset:21504
	s_waitcnt vmcnt(9) lgkmcnt(13)
	v_mfma_f32_32x32x16_bf16 v[18:33], v[228:231], v[74:77], v[18:33]
	ds_read_b128 v[228:231], v175 offset:544
	s_waitcnt lgkmcnt(13)
	v_mfma_f32_32x32x16_bf16 v[2:17], v[232:235], v[74:77], v[2:17]
	ds_read_b128 v[232:235], v175 offset:21536
	s_waitcnt vmcnt(8) lgkmcnt(13)
	v_mfma_f32_32x32x16_bf16 v[18:33], v[236:239], v[78:81], v[18:33]
	ds_read_b128 v[236:239], v175 offset:576
	s_waitcnt lgkmcnt(13)
	v_mfma_f32_32x32x16_bf16 v[2:17], v[240:243], v[78:81], v[2:17]
	ds_read_b128 v[240:243], v175 offset:608
	s_waitcnt vmcnt(7) lgkmcnt(13)
	v_mfma_f32_32x32x16_bf16 v[18:33], v[114:117], v[82:85], v[18:33]
	ds_read_b128 v[114:117], v175 offset:21568
	s_waitcnt lgkmcnt(13)
	v_mfma_f32_32x32x16_bf16 v[2:17], v[118:121], v[82:85], v[2:17]
	ds_read_b128 v[118:121], v175 offset:21600
	s_waitcnt vmcnt(6) lgkmcnt(13)
	v_mfma_f32_32x32x16_bf16 v[18:33], v[122:125], v[86:89], v[18:33]
	s_waitcnt lgkmcnt(12)
	v_mfma_f32_32x32x16_bf16 v[2:17], v[126:129], v[86:89], v[2:17]
	s_waitcnt vmcnt(5) lgkmcnt(11)
	v_mfma_f32_32x32x16_bf16 v[18:33], v[176:179], v[90:93], v[18:33]
	s_waitcnt lgkmcnt(10)
	v_mfma_f32_32x32x16_bf16 v[2:17], v[180:183], v[90:93], v[2:17]
	s_waitcnt vmcnt(4) lgkmcnt(9)
	v_mfma_f32_32x32x16_bf16 v[18:33], v[184:187], v[94:97], v[18:33]
	s_waitcnt lgkmcnt(8)
	v_mfma_f32_32x32x16_bf16 v[2:17], v[188:191], v[94:97], v[2:17]
	s_waitcnt vmcnt(3) lgkmcnt(7)
	v_mfma_f32_32x32x16_bf16 v[18:33], v[220:223], v[98:101], v[18:33]
	s_waitcnt lgkmcnt(6)
	v_mfma_f32_32x32x16_bf16 v[2:17], v[224:227], v[98:101], v[2:17]
	s_waitcnt vmcnt(2) lgkmcnt(5)
	v_mfma_f32_32x32x16_bf16 v[18:33], v[228:231], v[102:105], v[18:33]
	s_waitcnt lgkmcnt(4)
	v_mfma_f32_32x32x16_bf16 v[2:17], v[232:235], v[102:105], v[2:17]
	s_waitcnt vmcnt(1) lgkmcnt(3)
	v_mfma_f32_32x32x16_bf16 v[18:33], v[236:239], v[106:109], v[18:33]
	s_waitcnt vmcnt(0) lgkmcnt(2)
	v_mfma_f32_32x32x16_bf16 v[18:33], v[240:243], v[110:113], v[18:33]
	s_waitcnt lgkmcnt(1)
	v_mfma_f32_32x32x16_bf16 v[2:17], v[114:117], v[106:109], v[2:17]
	s_nop 9
	v_max3_f32 v175, v18, s8, v19
	v_max3_f32 v175, v175, v20, v21
	v_max3_f32 v175, v175, v22, v23
	v_max3_f32 v175, v175, v24, v25
	v_max3_f32 v175, v175, v26, v27
	v_max3_f32 v175, v175, v28, v29
	v_max3_f32 v175, v175, v30, v31
	s_waitcnt lgkmcnt(0)
	v_mfma_f32_32x32x16_bf16 v[2:17], v[118:121], v[110:113], v[2:17]
	v_max3_f32 v175, v175, v32, v33
	v_xor_b32_e32 v176, 32, v192
	v_add_u32_e32 v177, 64, v193
	v_cmp_lt_i32_e32 vcc, v176, v177
	s_and_b32 s8, s29, 4
	s_or_b32 s8, s8, s91
	v_cndmask_b32_e32 v176, v192, v176, vcc
	s_nop 4
	v_max3_f32 v175, v175, v2, v3
	v_max3_f32 v175, v175, v4, v5
	v_max3_f32 v175, v175, v6, v7
	v_max3_f32 v175, v175, v8, v9
	v_max3_f32 v175, v175, v10, v11
	v_max3_f32 v175, v175, v12, v13
	v_max3_f32 v175, v175, v14, v15
	v_max3_f32 v175, v175, v16, v17
	v_lshlrev_b32_e32 v176, 2, v176
	v_mov_b32_e32 v177, v175
	s_mulk_i32 s8, 0x1080
	s_add_i32 s8, s8, 0
	s_add_i32 s8, s8, 0x1ec00
	v_permlane32_swap_b32_e32 v177, v175
	v_max3_f32 v175, v165, v175, v177
	v_sub_f32_e32 v177, v175, v165
	v_cmp_lt_f32_e32 vcc, 8.0, v177
	s_nop 1
	v_cndmask_b32_e32 v175, v165, v175, vcc
	v_sub_f32_e32 v18, v18, v175
	v_exp_f32_e32 v18, v18
	v_sub_f32_e32 v19, v19, v175
	v_exp_f32_e32 v19, v19
	v_sub_f32_e32 v20, v20, v175
	v_exp_f32_e32 v20, v20
	v_sub_f32_e32 v21, v21, v175
	v_exp_f32_e32 v21, v21
	v_sub_f32_e32 v22, v22, v175
	v_add_f32_e32 v177, 0, v18
	v_exp_f32_e32 v22, v22
	v_sub_f32_e32 v23, v23, v175
	v_add_f32_e32 v177, v177, v19
	v_exp_f32_e32 v23, v23
	v_sub_f32_e32 v24, v24, v175
	v_add_f32_e32 v177, v177, v20
	v_exp_f32_e32 v24, v24
	v_sub_f32_e32 v25, v25, v175
	v_add_f32_e32 v177, v177, v21
	v_exp_f32_e32 v25, v25
	v_sub_f32_e32 v26, v26, v175
	v_add_f32_e32 v177, v177, v22
	v_exp_f32_e32 v26, v26
	v_sub_f32_e32 v27, v27, v175
	v_add_f32_e32 v177, v177, v23
	v_exp_f32_e32 v27, v27
	v_sub_f32_e32 v28, v28, v175
	v_add_f32_e32 v177, v177, v24
	v_exp_f32_e32 v28, v28
	v_sub_f32_e32 v29, v29, v175
	v_add_f32_e32 v177, v177, v25
	v_exp_f32_e32 v29, v29
	v_sub_f32_e32 v30, v30, v175
	v_add_f32_e32 v177, v177, v26
	v_exp_f32_e32 v30, v30
	v_sub_f32_e32 v31, v31, v175
	v_add_f32_e32 v177, v177, v27
	v_exp_f32_e32 v31, v31
	v_sub_f32_e32 v32, v32, v175
	v_add_f32_e32 v177, v177, v28
	v_exp_f32_e32 v32, v32
	v_sub_f32_e32 v33, v33, v175
	v_add_f32_e32 v177, v177, v29
	v_exp_f32_e32 v33, v33
	v_sub_f32_e32 v2, v2, v175
	v_add_f32_e32 v177, v177, v30
	v_exp_f32_e32 v178, v2
	v_sub_f32_e32 v2, v3, v175
	v_add_f32_e32 v177, v177, v31
	v_exp_f32_e32 v179, v2
	v_sub_f32_e32 v2, v4, v175
	v_add_f32_e32 v177, v177, v32
	v_exp_f32_e32 v180, v2
	v_sub_f32_e32 v2, v5, v175
	v_add_f32_e32 v177, v177, v33
	v_exp_f32_e32 v5, v2
	v_sub_f32_e32 v3, v6, v175
	v_add_f32_e32 v2, v177, v178
	v_exp_f32_e32 v177, v3
	v_sub_f32_e32 v3, v7, v175
	v_add_f32_e32 v2, v2, v179
	v_exp_f32_e32 v181, v3
	v_sub_f32_e32 v3, v8, v175
	v_add_f32_e32 v2, v2, v180
	v_exp_f32_e32 v182, v3
	v_sub_f32_e32 v3, v9, v175
	v_add_f32_e32 v2, v2, v5
	v_exp_f32_e32 v183, v3
	v_sub_f32_e32 v3, v10, v175
	v_add_f32_e32 v2, v2, v177
	v_exp_f32_e32 v10, v3
	v_sub_f32_e32 v3, v11, v175
	v_add_f32_e32 v2, v2, v181
	v_exp_f32_e32 v11, v3
	v_sub_f32_e32 v3, v12, v175
	v_add_f32_e32 v2, v2, v182
	v_exp_f32_e32 v12, v3
	v_sub_f32_e32 v3, v13, v175
	v_add_f32_e32 v2, v2, v183
	v_exp_f32_e32 v13, v3
	v_sub_f32_e32 v3, v14, v175
	v_add_f32_e32 v2, v2, v10
	v_exp_f32_e32 v14, v3
	v_sub_f32_e32 v3, v15, v175
	v_add_f32_e32 v2, v2, v11
	v_exp_f32_e32 v15, v3
	v_sub_f32_e32 v3, v16, v175
	v_add_f32_e32 v2, v2, v12
	v_exp_f32_e32 v16, v3
	v_sub_f32_e32 v3, v17, v175
	v_add_f32_e32 v2, v2, v13
	v_exp_f32_e32 v17, v3
	v_add_f32_e32 v2, v2, v14
	v_add_f32_e32 v2, v2, v15
	v_add_f32_e32 v2, v2, v16
	v_add_f32_e32 v2, v2, v17
	v_sub_f32_e32 v165, v165, v175
	v_mov_b32_e32 v4, v2
	v_exp_f32_e32 v3, v165
	v_add_u32_e32 v165, s8, v169
	v_permlane32_swap_b32_e32 v4, v2
	v_cvt_pk_bf16_f32 v6, v18, v19
	v_cvt_pk_bf16_f32 v7, v20, v21
	v_cvt_pk_bf16_f32 v8, v22, v23
	v_cvt_pk_bf16_f32 v9, v24, v25
	ds_write_b128 v165, v[6:9]
	v_cvt_pk_bf16_f32 v6, v26, v27
	v_cvt_pk_bf16_f32 v7, v28, v29
	v_cvt_pk_bf16_f32 v8, v30, v31
	v_cvt_pk_bf16_f32 v9, v32, v33
	ds_write_b128 v165, v[6:9] offset:1024
	v_cvt_pk_bf16_f32 v6, v178, v179
	v_cvt_pk_bf16_f32 v7, v180, v5
	v_cvt_pk_bf16_f32 v8, v177, v181
	v_cvt_pk_bf16_f32 v9, v182, v183
	ds_write_b128 v165, v[6:9] offset:2048
	v_cvt_pk_bf16_f32 v6, v10, v11
	v_cvt_pk_bf16_f32 v7, v12, v13
	v_cvt_pk_bf16_f32 v8, v14, v15
	v_cvt_pk_bf16_f32 v9, v16, v17
	ds_write_b128 v165, v[6:9] offset:3072
	s_and_saveexec_b64 s[16:17], s[4:5]
	v_add_u32_e32 v5, s8, v171
	ds_write_b32 v5, v3 offset:4096
	s_or_b64 exec, exec, s[16:17]
	s_waitcnt lgkmcnt(4)
	v_add_f32_e32 v2, v2, v4
	v_fmac_f32_e32 v2, v0, v3
	v_mov_b32_e32 v0, v2
	s_branch .LBB0_414
